# GEMM tile prologues: 128 accumulators zeroed with 64 v_mov_b64 instead of 128 v_mov_b32 (7 instances), on top of v45
# speedup vs baseline: 1.0032x; 1.0026x over previous
.LBB0_443:
	s_andn2_b64 vcc, exec, s[58:59]
	v_mov_b64_e32 v[18:19], 0
	v_mov_b64_e32 v[16:17], 0
	v_mov_b64_e32 v[22:23], 0
	v_mov_b64_e32 v[20:21], 0
	v_mov_b64_e32 v[130:131], 0
	v_mov_b64_e32 v[128:129], 0
	v_mov_b64_e32 v[134:135], 0
	v_mov_b64_e32 v[132:133], 0
	v_mov_b64_e32 v[114:115], 0
	v_mov_b64_e32 v[112:113], 0
	v_mov_b64_e32 v[118:119], 0
	v_mov_b64_e32 v[116:117], 0
	v_mov_b64_e32 v[98:99], 0
	v_mov_b64_e32 v[96:97], 0
	v_mov_b64_e32 v[102:103], 0
	v_mov_b64_e32 v[100:101], 0
	v_mov_b64_e32 v[26:27], 0
	v_mov_b64_e32 v[24:25], 0
	v_mov_b64_e32 v[30:31], 0
	v_mov_b64_e32 v[28:29], 0
	v_mov_b64_e32 v[138:139], 0
	v_mov_b64_e32 v[136:137], 0
	v_mov_b64_e32 v[142:143], 0
	v_mov_b64_e32 v[140:141], 0
	v_mov_b64_e32 v[122:123], 0
	v_mov_b64_e32 v[120:121], 0
	v_mov_b64_e32 v[126:127], 0
	v_mov_b64_e32 v[124:125], 0
	v_mov_b64_e32 v[106:107], 0
	v_mov_b64_e32 v[104:105], 0
	v_mov_b64_e32 v[110:111], 0
	v_mov_b64_e32 v[108:109], 0
	v_mov_b64_e32 v[82:83], 0
	v_mov_b64_e32 v[80:81], 0
	v_mov_b64_e32 v[86:87], 0
	v_mov_b64_e32 v[84:85], 0
	v_mov_b64_e32 v[66:67], 0
	v_mov_b64_e32 v[64:65], 0
	v_mov_b64_e32 v[70:71], 0
	v_mov_b64_e32 v[68:69], 0
	v_mov_b64_e32 v[50:51], 0
	v_mov_b64_e32 v[48:49], 0
	v_mov_b64_e32 v[54:55], 0
	v_mov_b64_e32 v[52:53], 0
	v_mov_b64_e32 v[38:39], 0
	v_mov_b64_e32 v[36:37], 0
	v_mov_b64_e32 v[42:43], 0
	v_mov_b64_e32 v[40:41], 0
	v_mov_b64_e32 v[90:91], 0
	v_mov_b64_e32 v[88:89], 0
	v_mov_b64_e32 v[94:95], 0
	v_mov_b64_e32 v[92:93], 0
	v_mov_b64_e32 v[74:75], 0
	v_mov_b64_e32 v[72:73], 0
	v_mov_b64_e32 v[78:79], 0
	v_mov_b64_e32 v[76:77], 0
	v_mov_b64_e32 v[58:59], 0
	v_mov_b64_e32 v[56:57], 0
	v_mov_b64_e32 v[62:63], 0
	v_mov_b64_e32 v[60:61], 0
	v_mov_b64_e32 v[46:47], 0
	v_mov_b64_e32 v[44:45], 0
	v_mov_b64_e32 v[34:35], 0
	v_mov_b64_e32 v[32:33], 0
	s_waitcnt vmcnt(0)
	s_cbranch_vccnz .LBB0_446
	s_add_u32 s14, s4, 0x40080
	s_addc_u32 s15, s5, 0
	s_add_u32 s11, s70, 0x100
	s_addc_u32 s13, s71, 0
	s_mov_b32 s4, 0

.LBB0_725:
	s_andn2_b64 vcc, exec, s[12:13]
	v_mov_b64_e32 v[122:123], 0
	v_mov_b64_e32 v[120:121], 0
	v_mov_b64_e32 v[126:127], 0
	v_mov_b64_e32 v[124:125], 0
	v_mov_b64_e32 v[110:111], 0
	v_mov_b64_e32 v[108:109], 0
	v_mov_b64_e32 v[106:107], 0
	v_mov_b64_e32 v[104:105], 0
	v_mov_b64_e32 v[94:95], 0
	v_mov_b64_e32 v[92:93], 0
	v_mov_b64_e32 v[90:91], 0
	v_mov_b64_e32 v[88:89], 0
	v_mov_b64_e32 v[78:79], 0
	v_mov_b64_e32 v[76:77], 0
	v_mov_b64_e32 v[74:75], 0
	v_mov_b64_e32 v[72:73], 0
	v_mov_b64_e32 v[118:119], 0
	v_mov_b64_e32 v[116:117], 0
	v_mov_b64_e32 v[114:115], 0
	v_mov_b64_e32 v[112:113], 0
	v_mov_b64_e32 v[102:103], 0
	v_mov_b64_e32 v[100:101], 0
	v_mov_b64_e32 v[98:99], 0
	v_mov_b64_e32 v[96:97], 0
	v_mov_b64_e32 v[86:87], 0
	v_mov_b64_e32 v[84:85], 0
	v_mov_b64_e32 v[82:83], 0
	v_mov_b64_e32 v[80:81], 0
	v_mov_b64_e32 v[70:71], 0
	v_mov_b64_e32 v[68:69], 0
	v_mov_b64_e32 v[66:67], 0
	v_mov_b64_e32 v[64:65], 0
	v_mov_b64_e32 v[62:63], 0
	v_mov_b64_e32 v[60:61], 0
	v_mov_b64_e32 v[58:59], 0
	v_mov_b64_e32 v[56:57], 0
	v_mov_b64_e32 v[46:47], 0
	v_mov_b64_e32 v[44:45], 0
	v_mov_b64_e32 v[42:43], 0
	v_mov_b64_e32 v[40:41], 0
	v_mov_b64_e32 v[30:31], 0
	v_mov_b64_e32 v[28:29], 0
	v_mov_b64_e32 v[26:27], 0
	v_mov_b64_e32 v[24:25], 0
	v_mov_b64_e32 v[14:15], 0
	v_mov_b64_e32 v[12:13], 0
	v_mov_b64_e32 v[10:11], 0
	v_mov_b64_e32 v[8:9], 0
	v_mov_b64_e32 v[54:55], 0
	v_mov_b64_e32 v[52:53], 0
	v_mov_b64_e32 v[50:51], 0
	v_mov_b64_e32 v[48:49], 0
	v_mov_b64_e32 v[38:39], 0
	v_mov_b64_e32 v[36:37], 0
	v_mov_b64_e32 v[34:35], 0
	v_mov_b64_e32 v[32:33], 0
	v_mov_b64_e32 v[22:23], 0
	v_mov_b64_e32 v[20:21], 0
	v_mov_b64_e32 v[18:19], 0
	v_mov_b64_e32 v[16:17], 0
	v_mov_b64_e32 v[6:7], 0
	v_mov_b64_e32 v[4:5], 0
	v_mov_b64_e32 v[2:3], 0
	v_mov_b64_e32 v[0:1], 0
	s_cbranch_vccnz .LBB0_728
	s_add_u32 s30, s4, 0x10080
	s_addc_u32 s31, s5, 0
	s_add_u32 s23, s34, 0x100
	s_addc_u32 s25, s35, 0
	s_mov_b32 s4, 0

.LBB0_1264:
	s_andn2_b64 vcc, exec, s[14:15]
	v_mov_b64_e32 v[122:123], 0
	v_mov_b64_e32 v[120:121], 0
	v_mov_b64_e32 v[126:127], 0
	v_mov_b64_e32 v[124:125], 0
	v_mov_b64_e32 v[110:111], 0
	v_mov_b64_e32 v[108:109], 0
	v_mov_b64_e32 v[106:107], 0
	v_mov_b64_e32 v[104:105], 0
	v_mov_b64_e32 v[94:95], 0
	v_mov_b64_e32 v[92:93], 0
	v_mov_b64_e32 v[90:91], 0
	v_mov_b64_e32 v[88:89], 0
	v_mov_b64_e32 v[78:79], 0
	v_mov_b64_e32 v[76:77], 0
	v_mov_b64_e32 v[74:75], 0
	v_mov_b64_e32 v[72:73], 0
	v_mov_b64_e32 v[118:119], 0
	v_mov_b64_e32 v[116:117], 0
	v_mov_b64_e32 v[114:115], 0
	v_mov_b64_e32 v[112:113], 0
	v_mov_b64_e32 v[102:103], 0
	v_mov_b64_e32 v[100:101], 0
	v_mov_b64_e32 v[98:99], 0
	v_mov_b64_e32 v[96:97], 0
	v_mov_b64_e32 v[86:87], 0
	v_mov_b64_e32 v[84:85], 0
	v_mov_b64_e32 v[82:83], 0
	v_mov_b64_e32 v[80:81], 0
	v_mov_b64_e32 v[70:71], 0
	v_mov_b64_e32 v[68:69], 0
	v_mov_b64_e32 v[66:67], 0
	v_mov_b64_e32 v[64:65], 0
	v_mov_b64_e32 v[62:63], 0
	v_mov_b64_e32 v[60:61], 0
	v_mov_b64_e32 v[58:59], 0
	v_mov_b64_e32 v[56:57], 0
	v_mov_b64_e32 v[46:47], 0
	v_mov_b64_e32 v[44:45], 0
	v_mov_b64_e32 v[42:43], 0
	v_mov_b64_e32 v[40:41], 0
	v_mov_b64_e32 v[30:31], 0
	v_mov_b64_e32 v[28:29], 0
	v_mov_b64_e32 v[26:27], 0
	v_mov_b64_e32 v[24:25], 0
	v_mov_b64_e32 v[14:15], 0
	v_mov_b64_e32 v[12:13], 0
	v_mov_b64_e32 v[10:11], 0
	v_mov_b64_e32 v[8:9], 0
	v_mov_b64_e32 v[54:55], 0
	v_mov_b64_e32 v[52:53], 0
	v_mov_b64_e32 v[50:51], 0
	v_mov_b64_e32 v[48:49], 0
	v_mov_b64_e32 v[38:39], 0
	v_mov_b64_e32 v[36:37], 0
	v_mov_b64_e32 v[34:35], 0
	v_mov_b64_e32 v[32:33], 0
	v_mov_b64_e32 v[22:23], 0
	v_mov_b64_e32 v[20:21], 0
	v_mov_b64_e32 v[18:19], 0
	v_mov_b64_e32 v[16:17], 0
	v_mov_b64_e32 v[6:7], 0
	v_mov_b64_e32 v[4:5], 0
	v_mov_b64_e32 v[2:3], 0
	v_mov_b64_e32 v[0:1], 0
	s_cbranch_vccnz .LBB0_1267
	s_add_u32 s30, s30, 0x20080
	s_addc_u32 s31, s31, 0
	s_add_u32 s21, s4, 0x100
	s_addc_u32 s23, s5, 0
	s_mov_b32 s4, 0

.LBB0_1368:
	s_andn2_b64 vcc, exec, s[18:19]
	v_mov_b64_e32 v[122:123], 0
	v_mov_b64_e32 v[120:121], 0
	v_mov_b64_e32 v[126:127], 0
	v_mov_b64_e32 v[124:125], 0
	v_mov_b64_e32 v[110:111], 0
	v_mov_b64_e32 v[108:109], 0
	v_mov_b64_e32 v[106:107], 0
	v_mov_b64_e32 v[104:105], 0
	v_mov_b64_e32 v[94:95], 0
	v_mov_b64_e32 v[92:93], 0
	v_mov_b64_e32 v[90:91], 0
	v_mov_b64_e32 v[88:89], 0
	v_mov_b64_e32 v[78:79], 0
	v_mov_b64_e32 v[76:77], 0
	v_mov_b64_e32 v[74:75], 0
	v_mov_b64_e32 v[72:73], 0
	v_mov_b64_e32 v[118:119], 0
	v_mov_b64_e32 v[116:117], 0
	v_mov_b64_e32 v[114:115], 0
	v_mov_b64_e32 v[112:113], 0
	v_mov_b64_e32 v[102:103], 0
	v_mov_b64_e32 v[100:101], 0
	v_mov_b64_e32 v[98:99], 0
	v_mov_b64_e32 v[96:97], 0
	v_mov_b64_e32 v[86:87], 0
	v_mov_b64_e32 v[84:85], 0
	v_mov_b64_e32 v[82:83], 0
	v_mov_b64_e32 v[80:81], 0
	v_mov_b64_e32 v[70:71], 0
	v_mov_b64_e32 v[68:69], 0
	v_mov_b64_e32 v[66:67], 0
	v_mov_b64_e32 v[64:65], 0
	v_mov_b64_e32 v[62:63], 0
	v_mov_b64_e32 v[60:61], 0
	v_mov_b64_e32 v[58:59], 0
	v_mov_b64_e32 v[56:57], 0
	v_mov_b64_e32 v[46:47], 0
	v_mov_b64_e32 v[44:45], 0
	v_mov_b64_e32 v[42:43], 0
	v_mov_b64_e32 v[40:41], 0
	v_mov_b64_e32 v[30:31], 0
	v_mov_b64_e32 v[28:29], 0
	v_mov_b64_e32 v[26:27], 0
	v_mov_b64_e32 v[24:25], 0
	v_mov_b64_e32 v[14:15], 0
	v_mov_b64_e32 v[12:13], 0
	v_mov_b64_e32 v[10:11], 0
	v_mov_b64_e32 v[8:9], 0
	v_mov_b64_e32 v[54:55], 0
	v_mov_b64_e32 v[52:53], 0
	v_mov_b64_e32 v[50:51], 0
	v_mov_b64_e32 v[48:49], 0
	v_mov_b64_e32 v[38:39], 0
	v_mov_b64_e32 v[36:37], 0
	v_mov_b64_e32 v[34:35], 0
	v_mov_b64_e32 v[32:33], 0
	v_mov_b64_e32 v[22:23], 0
	v_mov_b64_e32 v[20:21], 0
	v_mov_b64_e32 v[18:19], 0
	v_mov_b64_e32 v[16:17], 0
	v_mov_b64_e32 v[6:7], 0
	v_mov_b64_e32 v[4:5], 0
	v_mov_b64_e32 v[2:3], 0
	s_waitcnt lgkmcnt(0)
	v_mov_b64_e32 v[0:1], 0
	s_waitcnt vmcnt(0)
	s_cbranch_vccnz .LBB0_1371
	s_add_u32 s34, s4, 0x40080
	s_addc_u32 s35, s5, 0
	s_add_u32 s23, s36, 0x100
	s_addc_u32 s25, s37, 0
	s_mov_b32 s4, 0

.LBB0_1462:
	s_andn2_b64 vcc, exec, s[14:15]
	v_mov_b64_e32 v[118:119], 0
	v_mov_b64_e32 v[116:117], 0
	v_mov_b64_e32 v[114:115], 0
	v_mov_b64_e32 v[112:113], 0
	v_mov_b64_e32 v[102:103], 0
	v_mov_b64_e32 v[100:101], 0
	v_mov_b64_e32 v[98:99], 0
	v_mov_b64_e32 v[96:97], 0
	v_mov_b64_e32 v[86:87], 0
	v_mov_b64_e32 v[84:85], 0
	v_mov_b64_e32 v[82:83], 0
	v_mov_b64_e32 v[80:81], 0
	v_mov_b64_e32 v[70:71], 0
	v_mov_b64_e32 v[68:69], 0
	v_mov_b64_e32 v[66:67], 0
	v_mov_b64_e32 v[64:65], 0
	v_mov_b64_e32 v[126:127], 0
	v_mov_b64_e32 v[124:125], 0
	v_mov_b64_e32 v[122:123], 0
	v_mov_b64_e32 v[120:121], 0
	v_mov_b64_e32 v[110:111], 0
	v_mov_b64_e32 v[108:109], 0
	v_mov_b64_e32 v[106:107], 0
	v_mov_b64_e32 v[104:105], 0
	v_mov_b64_e32 v[94:95], 0
	v_mov_b64_e32 v[92:93], 0
	v_mov_b64_e32 v[90:91], 0
	v_mov_b64_e32 v[88:89], 0
	v_mov_b64_e32 v[78:79], 0
	v_mov_b64_e32 v[76:77], 0
	v_mov_b64_e32 v[74:75], 0
	v_mov_b64_e32 v[72:73], 0
	v_mov_b64_e32 v[54:55], 0
	v_mov_b64_e32 v[52:53], 0
	v_mov_b64_e32 v[50:51], 0
	v_mov_b64_e32 v[48:49], 0
	v_mov_b64_e32 v[38:39], 0
	v_mov_b64_e32 v[36:37], 0
	v_mov_b64_e32 v[34:35], 0
	v_mov_b64_e32 v[32:33], 0
	v_mov_b64_e32 v[22:23], 0
	v_mov_b64_e32 v[20:21], 0
	v_mov_b64_e32 v[18:19], 0
	v_mov_b64_e32 v[16:17], 0
	v_mov_b64_e32 v[6:7], 0
	v_mov_b64_e32 v[4:5], 0
	v_mov_b64_e32 v[2:3], 0
	v_mov_b64_e32 v[0:1], 0
	v_mov_b64_e32 v[62:63], 0
	v_mov_b64_e32 v[60:61], 0
	v_mov_b64_e32 v[58:59], 0
	v_mov_b64_e32 v[56:57], 0
	v_mov_b64_e32 v[46:47], 0
	v_mov_b64_e32 v[44:45], 0
	v_mov_b64_e32 v[42:43], 0
	v_mov_b64_e32 v[40:41], 0
	v_mov_b64_e32 v[30:31], 0
	v_mov_b64_e32 v[28:29], 0
	v_mov_b64_e32 v[26:27], 0
	v_mov_b64_e32 v[24:25], 0
	v_mov_b64_e32 v[14:15], 0
	v_mov_b64_e32 v[12:13], 0
	v_mov_b64_e32 v[10:11], 0
	v_mov_b64_e32 v[8:9], 0
	s_waitcnt vmcnt(0)
	s_cbranch_vccnz .LBB0_1465
	s_add_u32 s30, s4, 0x40080
	s_addc_u32 s31, s5, 0
	s_add_u32 s19, s34, 0x100
	s_addc_u32 s21, s35, 0
	s_mov_b32 s4, 0

.LBB0_1550:
	s_andn2_b64 vcc, exec, s[18:19]
	v_mov_b64_e32 v[122:123], 0
	v_mov_b64_e32 v[120:121], 0
	v_mov_b64_e32 v[126:127], 0
	v_mov_b64_e32 v[124:125], 0
	v_mov_b64_e32 v[110:111], 0
	v_mov_b64_e32 v[108:109], 0
	v_mov_b64_e32 v[106:107], 0
	v_mov_b64_e32 v[104:105], 0
	v_mov_b64_e32 v[94:95], 0
	v_mov_b64_e32 v[92:93], 0
	v_mov_b64_e32 v[90:91], 0
	v_mov_b64_e32 v[88:89], 0
	v_mov_b64_e32 v[78:79], 0
	v_mov_b64_e32 v[76:77], 0
	v_mov_b64_e32 v[74:75], 0
	v_mov_b64_e32 v[72:73], 0
	v_mov_b64_e32 v[118:119], 0
	v_mov_b64_e32 v[116:117], 0
	v_mov_b64_e32 v[114:115], 0
	v_mov_b64_e32 v[112:113], 0
	v_mov_b64_e32 v[102:103], 0
	v_mov_b64_e32 v[100:101], 0
	v_mov_b64_e32 v[98:99], 0
	v_mov_b64_e32 v[96:97], 0
	v_mov_b64_e32 v[86:87], 0
	v_mov_b64_e32 v[84:85], 0
	v_mov_b64_e32 v[82:83], 0
	v_mov_b64_e32 v[80:81], 0
	v_mov_b64_e32 v[70:71], 0
	v_mov_b64_e32 v[68:69], 0
	v_mov_b64_e32 v[66:67], 0
	v_mov_b64_e32 v[64:65], 0
	v_mov_b64_e32 v[62:63], 0
	v_mov_b64_e32 v[60:61], 0
	v_mov_b64_e32 v[58:59], 0
	v_mov_b64_e32 v[56:57], 0
	v_mov_b64_e32 v[46:47], 0
	v_mov_b64_e32 v[44:45], 0
	v_mov_b64_e32 v[42:43], 0
	v_mov_b64_e32 v[40:41], 0
	v_mov_b64_e32 v[30:31], 0
	v_mov_b64_e32 v[28:29], 0
	v_mov_b64_e32 v[26:27], 0
	v_mov_b64_e32 v[24:25], 0
	v_mov_b64_e32 v[14:15], 0
	v_mov_b64_e32 v[12:13], 0
	v_mov_b64_e32 v[10:11], 0
	v_mov_b64_e32 v[8:9], 0
	v_mov_b64_e32 v[54:55], 0
	v_mov_b64_e32 v[52:53], 0
	v_mov_b64_e32 v[50:51], 0
	v_mov_b64_e32 v[48:49], 0
	v_mov_b64_e32 v[38:39], 0
	v_mov_b64_e32 v[36:37], 0
	v_mov_b64_e32 v[34:35], 0
	v_mov_b64_e32 v[32:33], 0
	v_mov_b64_e32 v[22:23], 0
	v_mov_b64_e32 v[20:21], 0
	v_mov_b64_e32 v[18:19], 0
	v_mov_b64_e32 v[16:17], 0
	v_mov_b64_e32 v[6:7], 0
	v_mov_b64_e32 v[4:5], 0
	v_mov_b64_e32 v[2:3], 0
	s_waitcnt lgkmcnt(0)
	v_mov_b64_e32 v[0:1], 0
	s_waitcnt vmcnt(0)
	s_cbranch_vccnz .LBB0_1553
	s_add_u32 s26, s26, 0xb0080
	s_addc_u32 s27, s27, 0
	s_add_u32 s56, s4, 0x100
	s_addc_u32 s57, s5, 0
	s_mov_b32 s4, 0

.LBB0_1652:
	s_andn2_b64 vcc, exec, s[12:13]
	v_mov_b64_e32 v[126:127], 0
	v_mov_b64_e32 v[124:125], 0
	v_mov_b64_e32 v[122:123], 0
	v_mov_b64_e32 v[120:121], 0
	v_mov_b64_e32 v[110:111], 0
	v_mov_b64_e32 v[108:109], 0
	v_mov_b64_e32 v[106:107], 0
	v_mov_b64_e32 v[104:105], 0
	v_mov_b64_e32 v[94:95], 0
	v_mov_b64_e32 v[92:93], 0
	v_mov_b64_e32 v[90:91], 0
	v_mov_b64_e32 v[88:89], 0
	v_mov_b64_e32 v[78:79], 0
	v_mov_b64_e32 v[76:77], 0
	v_mov_b64_e32 v[74:75], 0
	v_mov_b64_e32 v[72:73], 0
	v_mov_b64_e32 v[118:119], 0
	v_mov_b64_e32 v[116:117], 0
	v_mov_b64_e32 v[114:115], 0
	v_mov_b64_e32 v[112:113], 0
	v_mov_b64_e32 v[102:103], 0
	v_mov_b64_e32 v[100:101], 0
	v_mov_b64_e32 v[98:99], 0
	v_mov_b64_e32 v[96:97], 0
	v_mov_b64_e32 v[86:87], 0
	v_mov_b64_e32 v[84:85], 0
	v_mov_b64_e32 v[82:83], 0
	v_mov_b64_e32 v[80:81], 0
	v_mov_b64_e32 v[70:71], 0
	v_mov_b64_e32 v[68:69], 0
	v_mov_b64_e32 v[66:67], 0
	v_mov_b64_e32 v[64:65], 0
	v_mov_b64_e32 v[62:63], 0
	v_mov_b64_e32 v[60:61], 0
	v_mov_b64_e32 v[58:59], 0
	v_mov_b64_e32 v[56:57], 0
	v_mov_b64_e32 v[46:47], 0
	v_mov_b64_e32 v[44:45], 0
	v_mov_b64_e32 v[42:43], 0
	v_mov_b64_e32 v[40:41], 0
	v_mov_b64_e32 v[30:31], 0
	v_mov_b64_e32 v[28:29], 0
	v_mov_b64_e32 v[26:27], 0
	v_mov_b64_e32 v[24:25], 0
	v_mov_b64_e32 v[14:15], 0
	v_mov_b64_e32 v[12:13], 0
	v_mov_b64_e32 v[10:11], 0
	v_mov_b64_e32 v[8:9], 0
	v_mov_b64_e32 v[54:55], 0
	v_mov_b64_e32 v[52:53], 0
	v_mov_b64_e32 v[50:51], 0
	v_mov_b64_e32 v[48:49], 0
	v_mov_b64_e32 v[38:39], 0
	v_mov_b64_e32 v[36:37], 0
	v_mov_b64_e32 v[34:35], 0
	v_mov_b64_e32 v[32:33], 0
	v_mov_b64_e32 v[22:23], 0
	v_mov_b64_e32 v[20:21], 0
	v_mov_b64_e32 v[18:19], 0
	v_mov_b64_e32 v[16:17], 0
	v_mov_b64_e32 v[6:7], 0
	v_mov_b64_e32 v[4:5], 0
	v_mov_b64_e32 v[2:3], 0
	v_mov_b64_e32 v[0:1], 0
	s_cbranch_vccnz .LBB0_1655
	s_add_u32 s28, s28, 0x40080
	s_addc_u32 s29, s29, 0
	s_add_u32 s17, s30, 0x100
	s_addc_u32 s19, s31, 0
	s_mov_b32 s30, 0
